# attention PV: V fragments read four ahead into four register buffers (counted lgkmcnt) instead of read-wait-2xMFMA
# speedup vs baseline: 1.0315x; 1.0081x over previous
; #define ATT_LOADR(KR, VR, kb) do { KR[0] = *(const u32x4*)(kbase + (size_t)((kb) * 64 + kr0) * 1536); KR[1] = *(const u32x4*)(kbase + (size_t)((kb) * 64 + kr0 + 32) * 1536); \
;         VR[0] = *(const u32x4*)(vbase + (size_t)vr0 * SEQ + (kb) * 64); VR[1] = *(const u32x4*)(vbase + (size_t)(vr0 + 64) * SEQ + (kb) * 64); } while (0)
; #define ATT_STORER(KR, VR, buf) do { LAS unsigned char* kb_ = lds + (buf) * ATT_BUF; LAS unsigned char* vb_ = kb_ + 64 * KP * 2; \
;         *(LAS u32x4*)(kb_ + (kr0 * KP + kc0 * 8) * 2) = KR[0]; *(LAS u32x4*)(kb_ + ((kr0 + 32) * KP + kc0 * 8) * 2) = KR[1]; \
;         *(LAS u32x4*)(vb_ + (vr0 * VP + vc0 * 8) * 2) = VR[0]; *(LAS u32x4*)(vb_ + ((vr0 + 64) * VP + vc0 * 8) * 2) = VR[1]; } while (0)
; __device__ __forceinline__ void attn_phase(const Params& p, int l, int wave, int lane, LAS unsigned char* lds, int early) {
;     ...
;         __syncthreads();
;         ATT_LOADR(kreg, vreg, 0); ATT_STORER(kreg, vreg, 0);
;         __syncthreads();
;         for (int kb = 0; kb <= kl; ++kb) {
;             if (kb < kl) ATT_LOADR(kreg, vreg, kb + 1);
;             ATT_COMPUTE(kb);
;             if (kb < kl) ATT_STORER(kreg, vreg, (kb + 1) & 1);
.LBB0_285:
	v_sub_f32_e32 v96, v96, v230
	v_sub_f32_e32 v97, v97, v230
	v_sub_f32_e32 v98, v98, v230
	v_sub_f32_e32 v99, v99, v230
	v_sub_f32_e32 v100, v100, v230
	v_sub_f32_e32 v101, v101, v230
	v_sub_f32_e32 v102, v102, v230
	v_sub_f32_e32 v103, v103, v230
	v_sub_f32_e32 v104, v104, v230
	v_sub_f32_e32 v105, v105, v230
	v_sub_f32_e32 v106, v106, v230
	v_sub_f32_e32 v107, v107, v230
	v_sub_f32_e32 v108, v108, v230
	v_sub_f32_e32 v109, v109, v230
	v_sub_f32_e32 v110, v110, v230
	v_sub_f32_e32 v111, v111, v230
	v_exp_f32_e32 v96, v96
	v_exp_f32_e32 v97, v97
	v_exp_f32_e32 v98, v98
	v_exp_f32_e32 v99, v99
	v_exp_f32_e32 v100, v100
	v_exp_f32_e32 v101, v101
	v_exp_f32_e32 v102, v102
	v_exp_f32_e32 v103, v103
	v_exp_f32_e32 v104, v104
	v_exp_f32_e32 v105, v105
	v_exp_f32_e32 v106, v106
	v_exp_f32_e32 v107, v107
	v_exp_f32_e32 v108, v108
	v_exp_f32_e32 v109, v109
	v_exp_f32_e32 v110, v110
	v_exp_f32_e32 v111, v111
	v_cvt_pk_bf16_f32 v138, v96, v97
	v_cvt_pk_bf16_f32 v139, v98, v99
	v_cvt_pk_bf16_f32 v140, v100, v101
	v_cvt_pk_bf16_f32 v141, v102, v103
	v_cvt_pk_bf16_f32 v232, v104, v105
	v_cvt_pk_bf16_f32 v233, v106, v107
	v_cvt_pk_bf16_f32 v234, v108, v109
	v_cvt_pk_bf16_f32 v235, v110, v111
	s_setprio 1
	v_add_u32_e32 v220, s25, v168
	v_add_u32_e32 v231, v220, v211
	v_add_u32_e32 v243, v220, v212
	v_add_u32_e32 v220, v220, v213
	v_add_u32_e32 v240, 0x4000, v231
	v_add_u32_e32 v241, 0x4800, v231
	v_add_u32_e32 v242, 0x5000, v231
	v_add_u32_e32 v244, 0x6800, v231
	v_add_u32_e32 v245, 0x7000, v231
	v_add_u32_e32 v231, 0x7800, v231
	v_add_u32_e32 v243, 0x4000, v243
	v_add_u32_e32 v220, 0x4000, v220
	ds_read2_b64 v[236:239], v240 offset0:128 offset1:132
	ds_read2_b64 v[184:187], v241 offset0:160 offset1:164
	ds_read2_b64 v[188:191], v242 offset0:192 offset1:196
	ds_read2_b64 v[196:199], v243 offset0:128 offset1:132
	s_waitcnt lgkmcnt(3)
	v_mfma_f32_16x16x32_bf16 v[60:63], v[236:239], v[116:119], v[60:63]
	v_mfma_f32_16x16x32_bf16 v[28:31], v[236:239], v[138:141], v[28:31]
	ds_read2_b64 v[236:239], v244 offset1:4
	s_waitcnt lgkmcnt(3)
	v_mfma_f32_16x16x32_bf16 v[56:59], v[184:187], v[116:119], v[56:59]
	v_mfma_f32_16x16x32_bf16 v[20:23], v[184:187], v[138:141], v[20:23]
	ds_read2_b64 v[184:187], v245 offset0:32 offset1:36
	s_waitcnt lgkmcnt(3)
	v_mfma_f32_16x16x32_bf16 v[52:55], v[188:191], v[116:119], v[52:55]
	v_mfma_f32_16x16x32_bf16 v[24:27], v[188:191], v[138:141], v[24:27]
	ds_read2_b64 v[188:191], v231 offset0:64 offset1:68
	s_waitcnt lgkmcnt(3)
	v_mfma_f32_16x16x32_bf16 v[48:51], v[196:199], v[116:119], v[48:51]
	v_mfma_f32_16x16x32_bf16 v[16:19], v[196:199], v[138:141], v[16:19]
	ds_read2_b64 v[196:199], v220 offset0:128 offset1:132
	s_waitcnt lgkmcnt(3)
	v_mfma_f32_16x16x32_bf16 v[44:47], v[236:239], v[116:119], v[44:47]
	v_mfma_f32_16x16x32_bf16 v[12:15], v[236:239], v[138:141], v[12:15]
	ds_read2_b64 v[236:239], v240 offset0:136 offset1:140
	s_waitcnt lgkmcnt(3)
	v_mfma_f32_16x16x32_bf16 v[40:43], v[184:187], v[116:119], v[40:43]
	v_mfma_f32_16x16x32_bf16 v[8:11], v[184:187], v[138:141], v[8:11]
	ds_read2_b64 v[184:187], v241 offset0:168 offset1:172
	s_waitcnt lgkmcnt(3)
	v_mfma_f32_16x16x32_bf16 v[36:39], v[188:191], v[116:119], v[36:39]
	v_mfma_f32_16x16x32_bf16 v[4:7], v[188:191], v[138:141], v[4:7]
	ds_read2_b64 v[188:191], v242 offset0:200 offset1:204
	s_waitcnt lgkmcnt(3)
	v_mfma_f32_16x16x32_bf16 v[32:35], v[196:199], v[116:119], v[32:35]
	v_mfma_f32_16x16x32_bf16 v[0:3], v[196:199], v[138:141], v[0:3]
	ds_read2_b64 v[196:199], v243 offset0:136 offset1:140
	s_waitcnt lgkmcnt(3)
	v_mfma_f32_16x16x32_bf16 v[60:63], v[236:239], v[112:115], v[60:63]
	v_mfma_f32_16x16x32_bf16 v[28:31], v[236:239], v[232:235], v[28:31]
	ds_read2_b64 v[236:239], v244 offset0:8 offset1:12
	s_waitcnt lgkmcnt(3)
	v_mfma_f32_16x16x32_bf16 v[56:59], v[184:187], v[112:115], v[56:59]
	v_mfma_f32_16x16x32_bf16 v[20:23], v[184:187], v[232:235], v[20:23]
	ds_read2_b64 v[184:187], v245 offset0:40 offset1:44
	s_waitcnt lgkmcnt(3)
	v_mfma_f32_16x16x32_bf16 v[52:55], v[188:191], v[112:115], v[52:55]
	v_mfma_f32_16x16x32_bf16 v[24:27], v[188:191], v[232:235], v[24:27]
	ds_read2_b64 v[188:191], v231 offset0:72 offset1:76
	s_waitcnt lgkmcnt(3)
	v_mfma_f32_16x16x32_bf16 v[48:51], v[196:199], v[112:115], v[48:51]
	v_mfma_f32_16x16x32_bf16 v[16:19], v[196:199], v[232:235], v[16:19]
	ds_read2_b64 v[196:199], v220 offset0:136 offset1:140
	s_waitcnt lgkmcnt(3)
	v_mfma_f32_16x16x32_bf16 v[44:47], v[236:239], v[112:115], v[44:47]
	v_mfma_f32_16x16x32_bf16 v[12:15], v[236:239], v[232:235], v[12:15]
	s_waitcnt lgkmcnt(2)
	v_mfma_f32_16x16x32_bf16 v[40:43], v[184:187], v[112:115], v[40:43]
	v_mfma_f32_16x16x32_bf16 v[8:11], v[184:187], v[232:235], v[8:11]
	s_waitcnt lgkmcnt(1)
	v_mfma_f32_16x16x32_bf16 v[36:39], v[188:191], v[112:115], v[36:39]
	v_mfma_f32_16x16x32_bf16 v[4:7], v[188:191], v[232:235], v[4:7]
	s_waitcnt lgkmcnt(0)
	v_mfma_f32_16x16x32_bf16 v[32:35], v[196:199], v[112:115], v[32:35]
	v_mfma_f32_16x16x32_bf16 v[0:3], v[196:199], v[232:235], v[0:3]
	s_setprio 0
	s_andn2_b64 vcc, exec, s[28:29]
	s_cbranch_vccnz .LBB0_287
	s_andn2_b32 s25, 1, s36
	s_mul_i32 s25, s25, 0x8c00
	s_add_i32 s25, s25, 0
	v_add_u32_e32 v112, s25, v170
	v_add_u32_e32 v113, s25, v171
	v_add_u32_e32 v114, s25, v172
	v_add_u32_e32 v115, s25, v173
	s_waitcnt vmcnt(3)
	ds_write_b128 v112, v[80:83]
	s_waitcnt vmcnt(2)
	ds_write_b128 v113, v[84:87]
	s_waitcnt vmcnt(1)
	ds_write_b128 v114, v[88:91] offset:17408
	s_waitcnt vmcnt(0)
	ds_write_b128 v115, v[92:95] offset:17408

; #define LAS __attribute__((address_space(3)))
; __device__ __forceinline__ void rwkv_combine(const Params& p, int bh, int wave, int lane, LAS unsigned char* lds) {
;     LAS float* xs = (LAS float*)lds;
;     LAS float* pw = (LAS float*)(lds + 16384 + wave * 2048);
;     const float* SEND = (const float*)(p.ws + WS_SEND) + (size_t)bh * 32 * 8192 + (size_t)(wave * 8) * 64 + lane; float* SIN = (float*)(p.ws + WS_SIN) + (size_t)bh * 32 * 4096 + (size_t)(wave * 8) * 64 + lane;
;     f32x2 s[32];
; #pragma unroll
;     for (int j = 0; j < 32; ++j) s[j] = (f32x2){0.f, 0.f};
;     float own[8], pj[4][8], sl[4][8];
; #pragma unroll
;     for (int jj = 0; jj < 8; ++jj) own[jj] = 0.f;
; #pragma unroll
;     for (int d = 0; d < 4; ++d)
; #pragma unroll
;         for (int jj = 0; jj < 8; ++jj) { pj[d][jj] = SEND[(size_t)d * 8192 + (64 + jj) * 64]; sl[d][jj] = SEND[(size_t)d * 8192 + jj * 64]; }
.LBB0_293:
	v_mov_b32_e32 v184, 0x358637bd
	v_mov_b32_e32 v185, 0x3a27c5ac
	v_mov_b32_e32 v186, 0x600
	v_mov_b32_e32 v187, 0x3ca908c9
	v_mov_b32_e32 v188, 0x3c0881c4
	v_mov_b32_e32 v189, 0xbab64f3b
	v_mov_b32_e32 v191, 0x1200
	v_mov_b64_e32 v[196:197], 0x560
	v_mov_b32_e32 v198, 0x3e38aa3b
	v_not_b32_e32 v199, 31
	s_and_b64 vcc, exec, s[16:17]
	s_cbranch_vccz .LBB0_308
	s_mov_b32 s6, s2
	s_lshl_b32 s18, s34, 11
	s_ashr_i32 s7, s6, 31
	s_lshl_b32 s14, s34, 3
	s_add_i32 s19, s18, 0
	s_lshl_b64 s[12:13], s[6:7], 20
	s_ashr_i32 s15, s14, 31
	s_lshl_b64 s[6:7], s[6:7], 19
	v_readlane_b32 s3, v251, 62
	s_add_u32 s16, s3, s12
	v_readlane_b32 s3, v251, 63
	s_addc_u32 s17, s3, s13
	s_lshl_b64 s[14:15], s[14:15], 8
	s_add_u32 s16, s16, s14
	s_addc_u32 s17, s17, s15
	v_lshlrev_b32_e32 v136, 2, v151
	v_lshl_add_u64 v[0:1], s[16:17], 0, v[136:137]
	s_movk_i32 s3, 0x4000
	v_add_co_u32_e32 v2, vcc, s3, v0
	s_mov_b32 s3, 0xc000
	s_nop 0
	v_addc_co_u32_e32 v3, vcc, 0, v1, vcc
	global_load_dword v82, v[2:3], off
	global_load_dword v83, v[2:3], off offset:256
	global_load_dword v84, v[2:3], off offset:512
	global_load_dword v85, v[2:3], off offset:768
	global_load_dword v86, v[2:3], off offset:1024
	global_load_dword v87, v[2:3], off offset:1280
	global_load_dword v88, v[2:3], off offset:1536
	global_load_dword v89, v[2:3], off offset:1792
	global_load_dword v124, v136, s[16:17]
	global_load_dword v131, v136, s[16:17] offset:256
	global_load_dword v130, v136, s[16:17] offset:512
	global_load_dword v129, v136, s[16:17] offset:768
	global_load_dword v128, v136, s[16:17] offset:1024
	global_load_dword v127, v136, s[16:17] offset:1280
	global_load_dword v126, v136, s[16:17] offset:1536
	global_load_dword v125, v136, s[16:17] offset:1792
	v_add_co_u32_e32 v2, vcc, s3, v0
	s_mov_b32 s3, 0x8000
	s_nop 0
	v_addc_co_u32_e32 v3, vcc, 0, v1, vcc
	v_add_co_u32_e32 v4, vcc, s3, v0
	s_mov_b32 s3, 0x14000
	s_nop 0
	v_addc_co_u32_e32 v5, vcc, 0, v1, vcc
	global_load_dword v90, v[2:3], off
	global_load_dword v91, v[2:3], off offset:256
	global_load_dword v92, v[2:3], off offset:512
	global_load_dword v93, v[2:3], off offset:768
	global_load_dword v94, v[2:3], off offset:1024
	global_load_dword v95, v[2:3], off offset:1280
	global_load_dword v96, v[2:3], off offset:1536
	global_load_dword v97, v[2:3], off offset:1792
	global_load_dword v148, v[4:5], off
	global_load_dword v147, v[4:5], off offset:256
	global_load_dword v146, v[4:5], off offset:512
	global_load_dword v145, v[4:5], off offset:768
	global_load_dword v144, v[4:5], off offset:1024
	global_load_dword v135, v[4:5], off offset:1280
	global_load_dword v134, v[4:5], off offset:1536
	global_load_dword v133, v[4:5], off offset:1792
	v_add_co_u32_e32 v2, vcc, s3, v0
	s_mov_b32 s3, 0x10000
	s_nop 0
	v_addc_co_u32_e32 v3, vcc, 0, v1, vcc
	v_add_co_u32_e32 v4, vcc, s3, v0
	s_mov_b32 s3, 0x1c000
	s_nop 0
	v_addc_co_u32_e32 v5, vcc, 0, v1, vcc
	global_load_dword v98, v[2:3], off
	global_load_dword v99, v[2:3], off offset:256
	global_load_dword v100, v[2:3], off offset:512
	global_load_dword v101, v[2:3], off offset:768
	global_load_dword v102, v[2:3], off offset:1024
	global_load_dword v103, v[2:3], off offset:1280
	global_load_dword v104, v[2:3], off offset:1536
	global_load_dword v105, v[2:3], off offset:1792
	global_load_dword v156, v[4:5], off
	global_load_dword v155, v[4:5], off offset:256
	global_load_dword v154, v[4:5], off offset:512
	global_load_dword v153, v[4:5], off offset:768
	global_load_dword v152, v[4:5], off offset:1024
	global_load_dword v151, v[4:5], off offset:1280
	global_load_dword v150, v[4:5], off offset:1536
	global_load_dword v149, v[4:5], off offset:1792
	v_add_co_u32_e32 v2, vcc, s3, v0
	s_mov_b32 s3, 0x18000
	s_nop 0
	v_addc_co_u32_e32 v3, vcc, 0, v1, vcc
	v_add_co_u32_e32 v8, vcc, s3, v0
	s_add_u32 s12, s12, s14
	s_nop 0
	v_addc_co_u32_e32 v9, vcc, 0, v1, vcc
	global_load_dword v106, v[2:3], off
	global_load_dword v107, v[2:3], off offset:256
	global_load_dword v108, v[2:3], off offset:512
	global_load_dword v111, v[2:3], off offset:768
	global_load_dword v112, v[2:3], off offset:1024
	global_load_dword v113, v[2:3], off offset:1280
	global_load_dword v114, v[2:3], off offset:1536
	global_load_dword v115, v[2:3], off offset:1792
	global_load_dword v7, v[8:9], off
	global_load_dword v6, v[8:9], off offset:256
	global_load_dword v5, v[8:9], off offset:512
	global_load_dword v4, v[8:9], off offset:768
	s_nop 0
	global_load_dword v3, v[8:9], off offset:1024
	global_load_dword v2, v[8:9], off offset:1280
	global_load_dword v1, v[8:9], off offset:1536
	global_load_dword v0, v[8:9], off offset:1792
	v_readlane_b32 s24, v252, 40
	s_addc_u32 s13, s13, s15
	v_readlane_b32 s26, v252, 42
	v_readlane_b32 s27, v252, 43
	s_add_u32 s12, s26, s12
	s_addc_u32 s13, s27, s13
	s_add_u32 s6, s6, s14
	s_addc_u32 s7, s7, s15
	s_add_u32 s14, s26, s6
	v_mov_b32_e32 v10, 0
	s_mov_b32 s20, 0
	s_waitcnt vmcnt(0)
	v_add_u32_e32 v109, s19, v136
	v_add_u32_e32 v110, 0, v136
	s_addc_u32 s15, s27, s7
	v_mov_b32_e32 v11, v10
	v_mov_b32_e32 v12, v10
	v_mov_b32_e32 v13, v10
	v_mov_b32_e32 v14, v10
	v_mov_b32_e32 v15, v10
	v_mov_b32_e32 v16, v10
	v_mov_b32_e32 v17, v10
	v_mov_b32_e32 v18, v10
	v_mov_b32_e32 v19, v10
	v_mov_b32_e32 v20, v10
	v_mov_b32_e32 v21, v10
	v_mov_b32_e32 v22, v10
	v_mov_b32_e32 v23, v10
	v_mov_b32_e32 v24, v10
	v_mov_b32_e32 v25, v10
	v_mov_b32_e32 v26, v10
	v_mov_b32_e32 v27, v10
	v_mov_b32_e32 v28, v10
	v_mov_b32_e32 v29, v10
	v_mov_b32_e32 v30, v10
	v_mov_b32_e32 v31, v10
	v_mov_b32_e32 v32, v10
	v_mov_b32_e32 v33, v10
	v_mov_b32_e32 v34, v10
	v_mov_b32_e32 v35, v10
	v_mov_b32_e32 v36, v10
	v_mov_b32_e32 v37, v10
	v_mov_b32_e32 v38, v10
	v_mov_b32_e32 v39, v10
	v_mov_b32_e32 v40, v10
	v_mov_b32_e32 v41, v10
	v_mov_b32_e32 v42, v10
	v_mov_b32_e32 v43, v10
	v_mov_b32_e32 v44, v10
	v_mov_b32_e32 v45, v10
	v_mov_b32_e32 v46, v10
	v_mov_b32_e32 v47, v10
	v_mov_b32_e32 v48, v10
	v_mov_b32_e32 v49, v10
	v_mov_b32_e32 v50, v10
	v_mov_b32_e32 v51, v10
	v_mov_b32_e32 v52, v10
	v_mov_b32_e32 v53, v10
	v_mov_b32_e32 v54, v10
	v_mov_b32_e32 v55, v10
	v_mov_b32_e32 v56, v10
	v_mov_b32_e32 v57, v10
	v_mov_b32_e32 v58, v10
	v_mov_b32_e32 v59, v10
	v_mov_b32_e32 v60, v10
	v_mov_b32_e32 v61, v10
	v_mov_b32_e32 v62, v10
	v_mov_b32_e32 v63, v10
	v_mov_b32_e32 v64, v10
	v_mov_b32_e32 v65, v10
	v_mov_b32_e32 v66, v10
	v_mov_b32_e32 v67, v10
	v_mov_b32_e32 v68, v10
	v_mov_b32_e32 v69, v10
	v_mov_b32_e32 v70, v10
	v_mov_b32_e32 v71, v10
	v_mov_b32_e32 v72, v10
	v_mov_b32_e32 v73, v10
	v_mov_b32_e32 v80, v10
	v_mov_b32_e32 v81, v10
	v_mov_b32_e32 v78, v10
	v_mov_b32_e32 v79, v10
	v_mov_b32_e32 v76, v10
	v_mov_b32_e32 v77, v10
	v_mov_b32_e32 v74, v10
	v_mov_b32_e32 v75, v10
	s_waitcnt vmcnt(48)
	v_mov_b32_e32 v116, v125
	v_mov_b32_e32 v117, v126
	v_mov_b32_e32 v118, v127
	v_mov_b32_e32 v119, v128
	v_mov_b32_e32 v120, v129
	v_mov_b32_e32 v121, v130
	v_mov_b32_e32 v122, v131
	v_mov_b32_e32 v123, v124
	v_readlane_b32 s25, v252, 41
	s_branch .LBB0_296
